# GEMM->attention transition: arrival counter read early (before group_arrive's store drain + barrier); group_wait starts with a register compare, poll loop only as fallback
# speedup vs baseline: 1.0067x; 1.0049x over previous
; __device__ __forceinline__ unsigned xb_ld(unsigned* p)              { return __hip_atomic_load(p, __ATOMIC_RELAXED, __HIP_MEMORY_SCOPE_AGENT); }
; __device__ __forceinline__ void group_arrive(unsigned* cnt) {
;     asm volatile("s_waitcnt vmcnt(0)" ::: "memory");
;     __syncthreads();
;     if (threadIdx.x == 0) __hip_atomic_fetch_add(cnt, 1u, __ATOMIC_RELAXED, __HIP_MEMORY_SCOPE_AGENT);
; }
; __device__ __forceinline__ void group_wait(unsigned* cnt, unsigned want, unsigned* bar) {
;     if (threadIdx.x == 0) {
;         unsigned sp = 0;
;         while (__hip_atomic_load(cnt, __ATOMIC_RELAXED, __HIP_MEMORY_SCOPE_AGENT) < want) {
;             __builtin_amdgcn_s_sleep(2);
;             if ((++sp & 255u) == 0u) { if (xb_ld(&bar[XB_TMO])) break; if (sp > XB_SPIN_CAP) { atomicAdd(&bar[XB_TMO], 1u); break; } }
;         }
;         __builtin_amdgcn_fence(__ATOMIC_ACQUIRE, "agent");
;         asm volatile("s_waitcnt vmcnt(0)" ::: "memory");
;     }
;     __syncthreads();
; }
; __global__ void __launch_bounds__(NWAVES * 64, 2) fwd_megakernel(Args a) {
;     ...
;         if (flow) {
;             group_arrive(gcc);
;             const int gb = blockIdx.x & 7, l = blockIdx.x >> 3;
;             if (l >= 8) {
;                 group_wait(gca, 256u, (unsigned*)(ws + WS_BAR));
.LBB0_253:
	s_and_b64 vcc, exec, s[0:1]
	s_cbranch_vccz .LBB0_339
	v_readlane_b32 s2, v253, 37
	v_readlane_b32 s3, v253, 38
	v_mov_b32_e32 v233, 0
	s_nop 3
	global_load_dword v232, v233, s[2:3] sc1
	v_readlane_b32 s0, v253, 36
	s_add_u32 s0, s96, s0
	s_addc_u32 s1, s97, 0
	s_waitcnt vmcnt(0)
	s_add_u32 s8, s0, 0x188000
	s_addc_u32 s9, s1, 0
	s_waitcnt vmcnt(0) lgkmcnt(0)
	s_barrier
	s_mov_b64 s[0:1], exec
	v_readlane_b32 s2, v253, 23
	v_readlane_b32 s3, v253, 24
	s_and_b64 s[2:3], s[0:1], s[2:3]
	s_mov_b64 exec, s[2:3]
	s_cbranch_execz .LBB0_257
	s_mov_b64 s[2:3], exec
	v_mbcnt_lo_u32_b32 v0, s2, 0
	v_mbcnt_hi_u32_b32 v0, s3, v0
	v_cmp_eq_u32_e32 vcc, 0, v0
	s_and_b64 s[4:5], exec, vcc
	s_mov_b64 exec, s[4:5]
	s_cbranch_execz .LBB0_257
	s_bcnt1_i32_b64 s2, s[2:3]
	v_mov_b32_e32 v0, 0
	v_mov_b32_e32 v1, s2
	global_atomic_add v0, v1, s[8:9]
.LBB0_257:
	s_or_b64 exec, exec, s[0:1]
	s_cmp_lt_u32 s98, 64
	s_cbranch_scc0 .LBB0_268
	s_mov_b64 s[0:1], exec
	v_readlane_b32 s2, v253, 23
	v_readlane_b32 s3, v253, 24
	s_and_b64 s[2:3], s[0:1], s[2:3]
	s_mov_b64 exec, s[2:3]
	s_cbranch_execz .LBB0_274
	v_readlane_b32 s2, v253, 37
	v_mov_b32_e32 v0, 0
	v_readlane_b32 s3, v253, 38
	s_movk_i32 s12, 0xff
	s_nop 3
	buffer_inv sc1
	v_cmp_lt_u32_e32 vcc, s12, v232
	s_cbranch_vccnz .LBB0_273
	global_load_dword v1, v0, s[2:3] sc1
	s_waitcnt vmcnt(0)
	v_cmp_lt_u32_e32 vcc, s12, v1
	s_cbranch_vccnz .LBB0_273
	s_add_u32 s2, s96, 0x180200
	s_addc_u32 s3, s97, 0
	s_mov_b32 s13, 1
	s_branch .LBB0_262

; __device__ __forceinline__ unsigned xb_ld(unsigned* p)              { return __hip_atomic_load(p, __ATOMIC_RELAXED, __HIP_MEMORY_SCOPE_AGENT); }
; __device__ __forceinline__ void group_wait(unsigned* cnt, unsigned want, unsigned* bar) {
;     if (threadIdx.x == 0) {
;         unsigned sp = 0;
;         while (__hip_atomic_load(cnt, __ATOMIC_RELAXED, __HIP_MEMORY_SCOPE_AGENT) < want) {
;             __builtin_amdgcn_s_sleep(2);
;             if ((++sp & 255u) == 0u) { if (xb_ld(&bar[XB_TMO])) break; if (sp > XB_SPIN_CAP) { atomicAdd(&bar[XB_TMO], 1u); break; } }
;         }
;         __builtin_amdgcn_fence(__ATOMIC_ACQUIRE, "agent");
;         asm volatile("s_waitcnt vmcnt(0)" ::: "memory");
;     }
;     __syncthreads();
; }
.LBB0_275:
	s_mov_b64 s[0:1], exec
	v_readlane_b32 s2, v253, 23
	v_readlane_b32 s3, v253, 24
	s_and_b64 s[2:3], s[0:1], s[2:3]
	s_mov_b64 exec, s[2:3]
	s_cbranch_execz .LBB0_290
	v_readlane_b32 s2, v253, 37
	v_mov_b32_e32 v0, 0
	v_readlane_b32 s3, v253, 38
	s_movk_i32 s12, 0xff
	s_nop 3
	buffer_inv sc1
	v_cmp_lt_u32_e32 vcc, s12, v232
	s_cbranch_vccnz .LBB0_289
	global_load_dword v1, v0, s[2:3] sc1
	s_waitcnt vmcnt(0)
	v_cmp_lt_u32_e32 vcc, s12, v1
	s_cbranch_vccnz .LBB0_289
	s_add_u32 s2, s96, 0x180200
	s_addc_u32 s3, s97, 0
	s_mov_b32 s13, 1
	s_branch .LBB0_279
